# mixer SB store_head: gain-vector loads for tile B removed (reuse tile A's registers), vmcnt re-derived; on top of stage B
# baseline (speedup 1.0000x reference)
; DI void store_head(const f32x16& o0, const f32x16& o1, float rs, const unsigned char* gl, int tr, int ch0, const float* gs, bf16_t* yp) {
;     u32x2 gt[8]; f32x4 gv[8];
; #pragma unroll
;     for (int q = 0; q < 8; ++q) { const int d = 32 * (q >> 2) + 8 * (q & 3); gt[q] = *(const u32x2*)(gl + gate_off(tr, ch0 + d)); gv[q] = *(const f32x4*)(gs + d); }
; #pragma unroll
; DI void mixer_phase(const Params& p, unsigned char* ldsraw, int vid) {
;     ...
;             float totA = 0.f, totB = 0.f;
; #pragma unroll
;             for (int w8 = 0; w8 < 8; ++w8) { totA += lf[w8 * 32 + r]; totB += lf[256 + w8 * 32 + r]; }
;             const float* gs = p.g_sb + 64 * wid + 4 * hh;
;             store_head(oA0, oA1, rsqrtf(totA * (1.0f / 512.0f) + EPS), gl, r, 64 * wid + 4 * hh, gs, Y + (size_t)tqA * 1024 + 64 * wid + 4 * hh);
;             store_head(oB0, oB1, rsqrtf(totB * (1.0f / 512.0f) + EPS), gl, r + 32, 64 * wid + 4 * hh, gs, Y + (size_t)tqB * 1024 + 64 * wid + 4 * hh);
.LBB0_414:
	s_or_b64 exec, exec, s[0:1]
	v_lshlrev_b32_e32 v144, 2, v176
	v_add_u32_e32 v158, s74, v144
	v_add_u32_e32 v70, 16, v158
	v_and_b32_e32 v160, 15, v205
	v_lshlrev_b32_e32 v71, 1, v70
	v_lshrrev_b32_e32 v70, 3, v70
	v_or_b32_e32 v96, s38, v206
	v_lshl_add_u32 v161, v206, 2, 0
	v_bitop3_b32 v70, v70, v160, 63 bitop3:0x6c
	v_add_u32_e32 v64, 0x400, v161
	v_ashrrev_i32_e32 v97, 31, v96
	v_and_b32_e32 v72, 0xfffffc00, v71
	v_lshlrev_b32_e32 v70, 4, v70
	v_and_b32_e32 v138, 8, v71
	v_add_u32_e32 v71, 24, v158
	s_waitcnt vmcnt(0)
	s_waitcnt lgkmcnt(0)
	s_barrier
	ds_read2_b32 v[102:103], v161 offset1:32
	ds_read2_b32 v[110:111], v64 offset1:32
	ds_read2_b32 v[108:109], v161 offset0:64 offset1:96
	ds_read2_b32 v[112:113], v64 offset0:64 offset1:96
	ds_read2_b32 v[106:107], v161 offset0:128 offset1:160
	ds_read2_b32 v[114:115], v64 offset0:128 offset1:160
	ds_read2_b32 v[104:105], v161 offset0:192 offset1:224
	ds_read2_b32 v[116:117], v64 offset0:192 offset1:224
	v_ashrrev_i32_e32 v145, 31, v144
	v_lshlrev_b64 v[64:65], 11, v[96:97]
	v_add3_u32 v139, 0, v70, v72
	v_lshlrev_b32_e32 v72, 1, v71
	v_lshrrev_b32_e32 v71, 3, v71
	v_lshl_add_u64 v[64:65], s[80:81], 0, v[64:65]
	v_lshlrev_b64 v[100:101], 1, v[144:145]
	v_lshrrev_b32_e32 v66, 3, v158
	v_bitop3_b32 v71, v71, v160, 63 bitop3:0x6c
	v_lshl_add_u64 v[140:141], v[64:65], 0, v[100:101]
	v_lshlrev_b32_e32 v64, 1, v158
	v_bitop3_b32 v66, v66, v160, 63 bitop3:0x6c
	v_and_b32_e32 v73, 0xfffffc00, v72
	v_lshlrev_b32_e32 v71, 4, v71
	v_and_b32_e32 v146, 8, v72
	v_add_u32_e32 v72, 32, v158
	v_and_b32_e32 v65, 0xfffffc00, v64
	v_lshlrev_b32_e32 v66, 4, v66
	v_and_b32_e32 v134, 8, v64
	v_add_u32_e32 v64, 8, v158
	v_add3_u32 v147, 0, v71, v73
	v_lshlrev_b32_e32 v73, 1, v72
	v_lshrrev_b32_e32 v72, 3, v72
	v_add_u32_e32 v90, 48, v158
	v_add3_u32 v135, 0, v66, v65
	v_lshlrev_b32_e32 v65, 1, v64
	v_lshrrev_b32_e32 v64, 3, v64
	v_bitop3_b32 v72, v72, v160, 63 bitop3:0x6c
	v_lshlrev_b32_e32 v91, 1, v90
	v_lshrrev_b32_e32 v90, 3, v90
	v_bitop3_b32 v64, v64, v160, 63 bitop3:0x6c
	v_and_b32_e32 v74, 0xfffffc00, v73
	v_lshlrev_b32_e32 v72, 4, v72
	v_bitop3_b32 v90, v90, v160, 63 bitop3:0x6c
	v_lshlrev_b32_e32 v159, 11, v206
	v_and_b32_e32 v66, 0xfffffc00, v65
	v_lshlrev_b32_e32 v64, 4, v64
	v_add3_u32 v149, 0, v72, v74
	v_add_u32_e32 v72, 40, v158
	v_and_b32_e32 v92, 0xfffffc00, v91
	v_lshlrev_b32_e32 v90, 4, v90
	v_and_b32_e32 v152, 8, v91
	v_add_u32_e32 v91, 56, v158
	v_lshl_add_u64 v[98:99], v[144:145], 2, s[56:57]
	v_add3_u32 v68, v135, v159, v134
	v_and_b32_e32 v136, 8, v65
	v_add3_u32 v137, 0, v64, v66
	v_and_b32_e32 v148, 8, v73
	v_lshlrev_b32_e32 v73, 1, v72
	v_lshrrev_b32_e32 v72, 3, v72
	v_add3_u32 v153, 0, v90, v92
	v_lshlrev_b32_e32 v92, 1, v91
	v_lshrrev_b32_e32 v91, 3, v91
	v_add3_u32 v69, v137, v159, v136
	global_load_dwordx4 v[192:195], v[98:99], off
	global_load_dwordx4 v[196:199], v[98:99], off offset:32
	v_add3_u32 v70, v139, v159, v138
	v_add3_u32 v71, v147, v159, v146
	ds_read_b64 v[118:119], v68 offset:4096
	ds_read_b64 v[124:125], v69 offset:4096
	ds_read_b64 v[128:129], v70 offset:4096
	ds_read_b64 v[142:143], v71 offset:4096
	v_bitop3_b32 v72, v72, v160, 63 bitop3:0x6c
	v_bitop3_b32 v91, v91, v160, 63 bitop3:0x6c
	v_and_b32_e32 v74, 0xfffffc00, v73
	v_lshlrev_b32_e32 v72, 4, v72
	v_and_b32_e32 v93, 0xfffffc00, v92
	v_lshlrev_b32_e32 v91, 4, v91
	v_add3_u32 v88, v149, v159, v148
	v_and_b32_e32 v150, 8, v73
	v_add3_u32 v151, 0, v72, v74
	v_and_b32_e32 v154, 8, v92
	v_add3_u32 v155, 0, v91, v93
	s_waitcnt lgkmcnt(3)
	v_lshlrev_b32_e32 v120, 16, v118
	global_load_dwordx4 v[208:211], v[98:99], off offset:64
	global_load_dwordx4 v[212:215], v[98:99], off offset:96
	v_add3_u32 v89, v151, v159, v150
	global_load_dwordx4 v[216:219], v[98:99], off offset:128
	global_load_dwordx4 v[220:223], v[98:99], off offset:160
	v_add3_u32 v90, v153, v159, v152
	v_add3_u32 v91, v155, v159, v154
	ds_read_b64 v[156:157], v88 offset:4096
	ds_read_b64 v[162:163], v89 offset:4096
	ds_read_b64 v[130:131], v90 offset:4096
	ds_read_b64 v[122:123], v91 offset:4096
	v_and_b32_e32 v121, 0xffff0000, v118
	v_mul_f32_e32 v88, 0xbfb8aa3b, v120
	v_exp_f32_e32 v118, v88
	v_mul_f32_e32 v88, 0xbfb8aa3b, v121
	v_exp_f32_e32 v127, v88
	v_lshlrev_b32_e32 v132, 16, v119
	v_add_f32_e32 v118, 1.0, v118
	v_rcp_f32_e32 v126, v118
	v_add_f32_e32 v118, 1.0, v127
	v_rcp_f32_e32 v127, v118
	v_and_b32_e32 v133, 0xffff0000, v119
	v_mul_f32_e32 v118, 0xbfb8aa3b, v132
	v_exp_f32_e32 v164, v118
	v_mul_f32_e32 v118, 0xbfb8aa3b, v133
	v_exp_f32_e32 v165, v118
	v_pk_mul_f32 v[118:119], v[126:127], v[120:121]
	s_waitcnt lgkmcnt(6)
	v_lshlrev_b32_e32 v126, 16, v124
	v_and_b32_e32 v127, 0xffff0000, v124
	v_mul_f32_e32 v124, 0xbfb8aa3b, v126
	v_add_f32_e32 v120, 1.0, v164
	v_add_f32_e32 v121, 1.0, v165
	v_exp_f32_e32 v124, v124
	v_mul_f32_e32 v164, 0xbfb8aa3b, v127
	v_rcp_f32_e32 v120, v120
	v_rcp_f32_e32 v121, v121
	v_exp_f32_e32 v164, v164
	v_add_f32_e32 v124, 1.0, v124
	v_and_b32_e32 v165, 0xffff0000, v125
	v_pk_mul_f32 v[120:121], v[120:121], v[132:133]
	v_rcp_f32_e32 v132, v124
	v_add_f32_e32 v124, 1.0, v164
	v_lshlrev_b32_e32 v164, 16, v125
	v_rcp_f32_e32 v133, v124
	v_mul_f32_e32 v124, 0xbfb8aa3b, v164
	v_exp_f32_e32 v166, v124
	v_mul_f32_e32 v124, 0xbfb8aa3b, v165
	global_load_dwordx4 v[224:227], v[98:99], off offset:192
	global_load_dwordx4 v[228:231], v[98:99], off offset:224
	v_exp_f32_e32 v167, v124
	v_pk_mul_f32 v[124:125], v[132:133], v[126:127]
	s_waitcnt lgkmcnt(5)
; DI unsigned pk_bf16(float lo, float hi) { f32x2 v = {lo, hi}; bf2_t b = __builtin_convertvector(v, bf2_t); return __builtin_bit_cast(unsigned, b); }
; DI float bf_lo(unsigned u) { return __uint_as_float(u << 16); }
; DI float bf_hi(unsigned u) { return __uint_as_float(u & 0xffff0000u); }
; DI float silu(float x) { return x * __builtin_amdgcn_rcpf(1.0f + __builtin_amdgcn_exp2f(-1.4426950408889634f * x)); }
; DI void store_head(const f32x16& o0, const f32x16& o1, float rs, const unsigned char* gl, int tr, int ch0, const float* gs, bf16_t* yp) {
;     u32x2 gt[8]; f32x4 gv[8];
; #pragma unroll
;     for (int q = 0; q < 8; ++q) { const int d = 32 * (q >> 2) + 8 * (q & 3); gt[q] = *(const u32x2*)(gl + gate_off(tr, ch0 + d)); gv[q] = *(const f32x4*)(gs + d); }
; #pragma unroll
;     for (int q = 0; q < 8; ++q) { const int d = 32 * (q >> 2) + 8 * (q & 3), g = q & 3;
;         const f32x16& o = (q >> 2) ? o1 : o0;
;         u32x2 w; w.x = pk_bf16(o[4 * g + 0] * rs * gv[q][0] * silu(bf_lo(gt[q].x)), o[4 * g + 1] * rs * gv[q][1] * silu(bf_hi(gt[q].x)));
;         w.y = pk_bf16(o[4 * g + 2] * rs * gv[q][2] * silu(bf_lo(gt[q].y)), o[4 * g + 3] * rs * gv[q][3] * silu(bf_hi(gt[q].y)));
;         *(u32x2*)(yp + d) = w; }
; DI void mixer_phase(const Params& p, unsigned char* ldsraw, int vid) {
;     ...
;             for (int w8 = 0; w8 < 8; ++w8) { totA += lf[w8 * 32 + r]; totB += lf[256 + w8 * 32 + r]; }
;             const float* gs = p.g_sb + 64 * wid + 4 * hh;
;             store_head(oA0, oA1, rsqrtf(totA * (1.0f / 512.0f) + EPS), gl, r, 64 * wid + 4 * hh, gs, Y + (size_t)tqA * 1024 + 64 * wid + 4 * hh);
	v_lshlrev_b32_e32 v132, 16, v128
	v_and_b32_e32 v133, 0xffff0000, v128
	v_mul_f32_e32 v128, 0xbfb8aa3b, v132
	v_add_f32_e32 v126, 1.0, v166
	v_add_f32_e32 v127, 1.0, v167
	v_exp_f32_e32 v128, v128
	v_mul_f32_e32 v166, 0xbfb8aa3b, v133
	v_rcp_f32_e32 v126, v126
	v_rcp_f32_e32 v127, v127
	v_exp_f32_e32 v166, v166
	v_add_f32_e32 v128, 1.0, v128
	v_and_b32_e32 v167, 0xffff0000, v129
	v_pk_mul_f32 v[126:127], v[126:127], v[164:165]
	v_rcp_f32_e32 v164, v128
	v_add_f32_e32 v128, 1.0, v166
	v_lshlrev_b32_e32 v166, 16, v129
	v_rcp_f32_e32 v165, v128
	v_mul_f32_e32 v128, 0xbfb8aa3b, v166
	v_exp_f32_e32 v168, v128
	v_mul_f32_e32 v128, 0xbfb8aa3b, v167
	v_exp_f32_e32 v169, v128
	v_pk_mul_f32 v[128:129], v[164:165], v[132:133]
	s_waitcnt lgkmcnt(4)
	v_lshlrev_b32_e32 v164, 16, v142
	v_and_b32_e32 v165, 0xffff0000, v142
	v_mul_f32_e32 v142, 0xbfb8aa3b, v164
	v_add_f32_e32 v132, 1.0, v168
	v_add_f32_e32 v133, 1.0, v169
	v_exp_f32_e32 v142, v142
	v_mul_f32_e32 v168, 0xbfb8aa3b, v165
	v_rcp_f32_e32 v132, v132
	v_rcp_f32_e32 v133, v133
	v_exp_f32_e32 v168, v168
	v_add_f32_e32 v142, 1.0, v142
	v_mov_b32_e32 v188, v110
	v_pk_mul_f32 v[132:133], v[132:133], v[166:167]
	v_rcp_f32_e32 v166, v142
	v_add_f32_e32 v142, 1.0, v168
	v_rcp_f32_e32 v167, v142
	v_lshlrev_b32_e32 v142, 16, v143
	v_and_b32_e32 v143, 0xffff0000, v143
	v_mul_f32_e32 v168, 0xbfb8aa3b, v142
	v_exp_f32_e32 v168, v168
	v_mul_f32_e32 v169, 0xbfb8aa3b, v143
	v_exp_f32_e32 v169, v169
	v_pk_mul_f32 v[164:165], v[166:167], v[164:165]
	v_add_f32_e32 v166, 1.0, v168
	s_waitcnt lgkmcnt(3)
	v_lshlrev_b32_e32 v168, 16, v156
	v_add_f32_e32 v167, 1.0, v169
	v_and_b32_e32 v169, 0xffff0000, v156
	v_mul_f32_e32 v156, 0xbfb8aa3b, v168
	v_exp_f32_e32 v156, v156
	v_mul_f32_e32 v170, 0xbfb8aa3b, v169
	v_rcp_f32_e32 v166, v166
	v_rcp_f32_e32 v167, v167
	v_exp_f32_e32 v170, v170
	v_add_f32_e32 v156, 1.0, v156
	v_mov_b32_e32 v189, v102
	v_pk_mul_f32 v[142:143], v[166:167], v[142:143]
	v_rcp_f32_e32 v166, v156
	v_add_f32_e32 v156, 1.0, v170
	v_rcp_f32_e32 v167, v156
	v_lshlrev_b32_e32 v156, 16, v157
	v_and_b32_e32 v157, 0xffff0000, v157
	v_mul_f32_e32 v170, 0xbfb8aa3b, v156
	v_exp_f32_e32 v170, v170
	v_mul_f32_e32 v171, 0xbfb8aa3b, v157
	v_exp_f32_e32 v171, v171
	v_pk_mul_f32 v[166:167], v[166:167], v[168:169]
	v_add_f32_e32 v168, 1.0, v170
	s_waitcnt lgkmcnt(2)
	v_lshlrev_b32_e32 v170, 16, v162
	v_add_f32_e32 v169, 1.0, v171
	v_and_b32_e32 v171, 0xffff0000, v162
	v_mul_f32_e32 v162, 0xbfb8aa3b, v170
	v_exp_f32_e32 v162, v162
	v_mul_f32_e32 v172, 0xbfb8aa3b, v171
	v_rcp_f32_e32 v168, v168
	v_rcp_f32_e32 v169, v169
	v_exp_f32_e32 v172, v172
	v_add_f32_e32 v162, 1.0, v162
	v_pk_add_f32 v[188:189], v[188:189], 0 op_sel_hi:[1,0]
	v_pk_mul_f32 v[156:157], v[168:169], v[156:157]
	v_rcp_f32_e32 v168, v162
	v_add_f32_e32 v162, 1.0, v172
	v_rcp_f32_e32 v169, v162
	v_lshlrev_b32_e32 v162, 16, v163
	v_and_b32_e32 v163, 0xffff0000, v163
	v_mul_f32_e32 v172, 0xbfb8aa3b, v162
	v_exp_f32_e32 v172, v172
	v_mul_f32_e32 v173, 0xbfb8aa3b, v163
	v_exp_f32_e32 v173, v173
	v_mov_b32_e32 v102, v111
	v_pk_add_f32 v[102:103], v[188:189], v[102:103]
	v_mov_b32_e32 v110, v112
	v_mov_b32_e32 v111, v108
	v_pk_add_f32 v[102:103], v[102:103], v[110:111]
	v_mov_b32_e32 v108, v113
	v_pk_mul_f32 v[168:169], v[168:169], v[170:171]
	v_add_f32_e32 v170, 1.0, v172
	s_waitcnt lgkmcnt(1)
	v_lshlrev_b32_e32 v172, 16, v130
	v_pk_add_f32 v[102:103], v[102:103], v[108:109]
	v_mov_b32_e32 v108, v114
	v_mov_b32_e32 v109, v106
	v_add_f32_e32 v171, 1.0, v173
	v_and_b32_e32 v173, 0xffff0000, v130
	v_mul_f32_e32 v130, 0xbfb8aa3b, v172
	v_pk_add_f32 v[102:103], v[102:103], v[108:109]
	v_mov_b32_e32 v106, v115
	v_exp_f32_e32 v130, v130
	v_mul_f32_e32 v174, 0xbfb8aa3b, v173
	v_pk_add_f32 v[102:103], v[102:103], v[106:107]
	v_mov_b32_e32 v106, v116
	v_mov_b32_e32 v107, v104
	v_rcp_f32_e32 v170, v170
	v_rcp_f32_e32 v171, v171
	v_exp_f32_e32 v174, v174
	v_pk_add_f32 v[102:103], v[102:103], v[106:107]
	v_mov_b32_e32 v104, v117
	v_pk_add_f32 v[102:103], v[102:103], v[104:105]
	s_mov_b32 s0, 0x3b000000
	v_pk_fma_f32 v[102:103], v[102:103], s[0:1], v[178:179] op_sel_hi:[1,0,0]
	v_add_f32_e32 v130, 1.0, v130
	v_mul_f32_e32 v104, 0x4b800000, v103
	v_cmp_gt_f32_e32 vcc, s98, v103
	v_pk_mul_f32 v[162:163], v[170:171], v[162:163]
	v_rcp_f32_e32 v170, v130
	v_add_f32_e32 v130, 1.0, v174
	v_cndmask_b32_e32 v103, v103, v104, vcc
	v_rcp_f32_e32 v171, v130
	v_lshlrev_b32_e32 v130, 16, v131
	v_and_b32_e32 v131, 0xffff0000, v131
	v_rsq_f32_e32 v103, v103
	v_mul_f32_e32 v175, 0xbfb8aa3b, v131
	v_exp_f32_e32 v175, v175
	v_mul_f32_e32 v174, 0xbfb8aa3b, v130
	v_exp_f32_e32 v174, v174
	v_mul_f32_e32 v110, 0x45800000, v103
	v_cndmask_b32_e32 v110, v103, v110, vcc
	v_pk_mul_f32 v[170:171], v[170:171], v[172:173]
	v_add_f32_e32 v173, 1.0, v175
	s_waitcnt lgkmcnt(0)
	v_and_b32_e32 v175, 0xffff0000, v122
	v_pk_mul_f32 v[48:49], v[48:49], v[110:111] op_sel_hi:[1,0]
	v_pk_mul_f32 v[50:51], v[50:51], v[110:111] op_sel_hi:[1,0]
	v_pk_mul_f32 v[32:33], v[32:33], v[110:111] op_sel_hi:[1,0]
	v_pk_mul_f32 v[34:35], v[34:35], v[110:111] op_sel_hi:[1,0]
	v_mul_f32_e32 v176, 0xbfb8aa3b, v175
	v_lshlrev_b32_e32 v184, 16, v123
	s_waitcnt vmcnt(7)
	v_pk_mul_f32 v[48:49], v[192:193], v[48:49]
	v_pk_mul_f32 v[50:51], v[194:195], v[50:51]
	s_waitcnt vmcnt(3)
; DI unsigned pk_bf16(float lo, float hi) { f32x2 v = {lo, hi}; bf2_t b = __builtin_convertvector(v, bf2_t); return __builtin_bit_cast(unsigned, b); }
; DI float bf_lo(unsigned u) { return __uint_as_float(u << 16); }
; DI float bf_hi(unsigned u) { return __uint_as_float(u & 0xffff0000u); }
; DI float silu(float x) { return x * __builtin_amdgcn_rcpf(1.0f + __builtin_amdgcn_exp2f(-1.4426950408889634f * x)); }
; DI void store_head(const f32x16& o0, const f32x16& o1, float rs, const unsigned char* gl, int tr, int ch0, const float* gs, bf16_t* yp) {
;     ...
;     for (int q = 0; q < 8; ++q) { const int d = 32 * (q >> 2) + 8 * (q & 3), g = q & 3;
;         const f32x16& o = (q >> 2) ? o1 : o0;
;         u32x2 w; w.x = pk_bf16(o[4 * g + 0] * rs * gv[q][0] * silu(bf_lo(gt[q].x)), o[4 * g + 1] * rs * gv[q][1] * silu(bf_hi(gt[q].x)));
;         w.y = pk_bf16(o[4 * g + 2] * rs * gv[q][2] * silu(bf_lo(gt[q].y)), o[4 * g + 3] * rs * gv[q][3] * silu(bf_hi(gt[q].y)));
;         *(u32x2*)(yp + d) = w; }
; DI void mixer_phase(const Params& p, unsigned char* ldsraw, int vid) {
;     ...
;             store_head(oB0, oB1, rsqrtf(totB * (1.0f / 512.0f) + EPS), gl, r + 32, 64 * wid + 4 * hh, gs, Y + (size_t)tqB * 1024 + 64 * wid + 4 * hh);
	v_pk_mul_f32 v[32:33], v[32:33], v[216:217]
	v_pk_mul_f32 v[34:35], v[34:35], v[218:219]
	v_add_f32_e32 v172, 1.0, v174
	v_lshlrev_b32_e32 v174, 16, v122
	v_exp_f32_e32 v176, v176
	v_and_b32_e32 v185, 0xffff0000, v123
	v_mul_f32_e32 v123, 0xbfb8aa3b, v184
	v_pk_mul_f32 v[48:49], v[48:49], v[118:119]
	v_pk_mul_f32 v[50:51], v[50:51], v[120:121]
	v_pk_mul_f32 v[32:33], v[32:33], v[166:167]
	v_pk_mul_f32 v[34:35], v[34:35], v[156:157]
	v_mul_f32_e32 v122, 0xbfb8aa3b, v174
	v_exp_f32_e32 v183, v123
	v_mul_f32_e32 v123, 0xbfb8aa3b, v185
	v_cvt_pk_bf16_f32 v236, v48, v49
	v_cvt_pk_bf16_f32 v237, v50, v51
	v_cvt_pk_bf16_f32 v244, v32, v33
	v_cvt_pk_bf16_f32 v245, v34, v35
	v_exp_f32_e32 v122, v122
	v_exp_f32_e32 v187, v123
	v_and_b32_e32 v252, 32, v205
	v_lshrrev_b32_e32 v252, 2, v252
	v_mov_b32_e32 v253, 0
	v_lshl_add_u64 v[254:255], v[140:141], 0, v[252:253]
	v_pk_mul_f32 v[48:49], v[52:53], v[110:111] op_sel_hi:[1,0]
	v_pk_mul_f32 v[50:51], v[54:55], v[110:111] op_sel_hi:[1,0]
	v_pk_mul_f32 v[32:33], v[36:37], v[110:111] op_sel_hi:[1,0]
	v_pk_mul_f32 v[34:35], v[38:39], v[110:111] op_sel_hi:[1,0]
	v_rcp_f32_e32 v172, v172
	v_rcp_f32_e32 v173, v173
	v_pk_mul_f32 v[48:49], v[196:197], v[48:49]
	v_pk_mul_f32 v[50:51], v[198:199], v[50:51]
	s_waitcnt vmcnt(2)
	v_pk_mul_f32 v[32:33], v[32:33], v[220:221]
	v_pk_mul_f32 v[34:35], v[34:35], v[222:223]
	v_add_f32_e32 v176, 1.0, v176
	v_pk_mul_f32 v[48:49], v[48:49], v[124:125]
	v_pk_mul_f32 v[50:51], v[50:51], v[126:127]
	v_pk_mul_f32 v[32:33], v[32:33], v[168:169]
	v_pk_mul_f32 v[34:35], v[34:35], v[162:163]
	v_rcp_f32_e32 v123, v176
	v_add_f32_e32 v176, 1.0, v183
	v_cvt_pk_bf16_f32 v238, v48, v49
	v_cvt_pk_bf16_f32 v239, v50, v51
	v_cvt_pk_bf16_f32 v246, v32, v33
	v_cvt_pk_bf16_f32 v247, v34, v35
	v_add_f32_e32 v122, 1.0, v122
	v_rcp_f32_e32 v186, v176
	v_add_f32_e32 v176, 1.0, v187
	s_nop 1
	v_permlane32_swap_b32_e32 v236, v238
	v_permlane32_swap_b32_e32 v237, v239
	global_store_dwordx4 v[254:255], v[236:239], off
	v_pk_mul_f32 v[48:49], v[56:57], v[110:111] op_sel_hi:[1,0]
	v_pk_mul_f32 v[50:51], v[58:59], v[110:111] op_sel_hi:[1,0]
	s_nop 1
	v_permlane32_swap_b32_e32 v244, v246
	v_permlane32_swap_b32_e32 v245, v247
	global_store_dwordx4 v[254:255], v[244:247], off offset:64
	v_pk_mul_f32 v[32:33], v[40:41], v[110:111] op_sel_hi:[1,0]
	v_pk_mul_f32 v[34:35], v[42:43], v[110:111] op_sel_hi:[1,0]
	v_rcp_f32_e32 v122, v122
	v_rcp_f32_e32 v187, v176
	v_pk_mul_f32 v[104:105], v[172:173], v[130:131]
	v_pk_mul_f32 v[48:49], v[208:209], v[48:49]
	v_pk_mul_f32 v[50:51], v[210:211], v[50:51]
	s_waitcnt vmcnt(3)
	v_pk_mul_f32 v[32:33], v[32:33], v[224:225]
	v_pk_mul_f32 v[34:35], v[34:35], v[226:227]
	v_pk_mul_f32 v[48:49], v[48:49], v[128:129]
	v_pk_mul_f32 v[50:51], v[50:51], v[132:133]
	v_pk_mul_f32 v[32:33], v[32:33], v[170:171]
	v_pk_mul_f32 v[34:35], v[34:35], v[104:105]
	v_cvt_pk_bf16_f32 v240, v48, v49
	v_cvt_pk_bf16_f32 v241, v50, v51
	v_cvt_pk_bf16_f32 v248, v32, v33
	v_cvt_pk_bf16_f32 v249, v34, v35
	v_pk_mul_f32 v[48:49], v[60:61], v[110:111] op_sel_hi:[1,0]
	v_pk_mul_f32 v[50:51], v[62:63], v[110:111] op_sel_hi:[1,0]
	v_pk_mul_f32 v[32:33], v[44:45], v[110:111] op_sel_hi:[1,0]
	v_pk_mul_f32 v[34:35], v[46:47], v[110:111] op_sel_hi:[1,0]
	v_pk_mul_f32 v[106:107], v[122:123], v[174:175]
	v_pk_mul_f32 v[108:109], v[186:187], v[184:185]
	v_pk_mul_f32 v[48:49], v[48:49], v[212:213]
	v_pk_mul_f32 v[50:51], v[50:51], v[214:215]
	s_waitcnt vmcnt(2)
	v_pk_mul_f32 v[32:33], v[32:33], v[228:229]
	v_pk_mul_f32 v[34:35], v[34:35], v[230:231]
	v_pk_mul_f32 v[48:49], v[48:49], v[164:165]
	v_pk_mul_f32 v[50:51], v[50:51], v[142:143]
	v_pk_mul_f32 v[32:33], v[32:33], v[106:107]
	v_pk_mul_f32 v[34:35], v[34:35], v[108:109]
	v_cvt_pk_bf16_f32 v242, v48, v49
	v_cvt_pk_bf16_f32 v243, v50, v51
	v_cvt_pk_bf16_f32 v250, v32, v33
	v_cvt_pk_bf16_f32 v251, v34, v35
	s_nop 1
	v_permlane32_swap_b32_e32 v240, v242
	v_permlane32_swap_b32_e32 v241, v243
	global_store_dwordx4 v[254:255], v[240:243], off offset:32
	s_nop 1
	v_permlane32_swap_b32_e32 v248, v250
	v_permlane32_swap_b32_e32 v249, v251
	global_store_dwordx4 v[254:255], v[248:251], off offset:96
	v_mul_f32_e32 v32, 0x4b800000, v102
	v_cmp_gt_f32_e32 vcc, s98, v102
	v_or_b32_e32 v162, 0x10000, v159
	v_add3_u32 v35, v147, v162, v146
	v_cndmask_b32_e32 v32, v102, v32, vcc
	v_rsq_f32_e32 v33, v32
	v_or_b32_e32 v32, 32, v96
	v_ashrrev_i32_e32 v163, 3, v205
	s_mov_b64 s[0:1], -1
	v_mul_f32_e32 v34, 0x45800000, v33
	v_cndmask_b32_e32 v48, v33, v34, vcc
	v_ashrrev_i32_e32 v33, 31, v32
	v_lshlrev_b64 v[32:33], 11, v[32:33]
	v_lshl_add_u64 v[32:33], s[80:81], 0, v[32:33]
	v_lshl_add_u64 v[142:143], v[32:33], 0, v[100:101]
	v_add3_u32 v32, v135, v162, v134
	v_add3_u32 v33, v137, v162, v136
	v_add3_u32 v34, v139, v162, v138
	ds_read_b64 v[72:73], v32 offset:4096
	ds_read_b64 v[74:75], v33 offset:4096
	ds_read_b64 v[76:77], v34 offset:4096
	ds_read_b64 v[78:79], v35 offset:4096
	s_waitcnt lgkmcnt(3)
	v_lshlrev_b32_e32 v80, 16, v72
	v_and_b32_e32 v81, 0xffff0000, v72
	v_mul_f32_e32 v36, 0xbfb8aa3b, v80
	v_exp_f32_e32 v36, v36
	v_mul_f32_e32 v37, 0xbfb8aa3b, v81
	v_exp_f32_e32 v37, v37
	v_add3_u32 v32, v149, v162, v148
	v_add3_u32 v33, v151, v162, v150
	v_add3_u32 v34, v153, v162, v152
	v_add3_u32 v35, v155, v162, v154
	ds_read_b64 v[82:83], v32 offset:4096
	ds_read_b64 v[54:55], v33 offset:4096
	ds_read_b64 v[52:53], v34 offset:4096
	ds_read_b64 v[50:51], v35 offset:4096
	v_add_f32_e32 v32, 1.0, v36
	v_rcp_f32_e32 v84, v32
	v_add_f32_e32 v32, 1.0, v37
	v_rcp_f32_e32 v85, v32
	v_lshlrev_b32_e32 v72, 16, v73
	v_pk_mul_f32 v[16:17], v[16:17], v[48:49] op_sel_hi:[1,0]
	v_and_b32_e32 v73, 0xffff0000, v73
	v_mul_f32_e32 v49, 0xbfb8aa3b, v72
	v_exp_f32_e32 v49, v49
	s_and_b64 vcc, exec, s[76:77]
	v_add_u32_e32 v146, s38, v163
	v_add_f32_e32 v49, 1.0, v49
	v_lshlrev_b32_e32 v164, 4, v163
	s_waitcnt vmcnt(4)
; DI unsigned pk_bf16(float lo, float hi) { f32x2 v = {lo, hi}; bf2_t b = __builtin_convertvector(v, bf2_t); return __builtin_bit_cast(unsigned, b); }
; DI float bf_lo(unsigned u) { return __uint_as_float(u << 16); }
; DI float bf_hi(unsigned u) { return __uint_as_float(u & 0xffff0000u); }
; DI float silu(float x) { return x * __builtin_amdgcn_rcpf(1.0f + __builtin_amdgcn_exp2f(-1.4426950408889634f * x)); }
; DI void store_head(const f32x16& o0, const f32x16& o1, float rs, const unsigned char* gl, int tr, int ch0, const float* gs, bf16_t* yp) {
;     ...
;     for (int q = 0; q < 8; ++q) { const int d = 32 * (q >> 2) + 8 * (q & 3), g = q & 3;
;         const f32x16& o = (q >> 2) ? o1 : o0;
;         u32x2 w; w.x = pk_bf16(o[4 * g + 0] * rs * gv[q][0] * silu(bf_lo(gt[q].x)), o[4 * g + 1] * rs * gv[q][1] * silu(bf_hi(gt[q].x)));
;         w.y = pk_bf16(o[4 * g + 2] * rs * gv[q][2] * silu(bf_lo(gt[q].y)), o[4 * g + 3] * rs * gv[q][3] * silu(bf_hi(gt[q].y)));
;         *(u32x2*)(yp + d) = w; }
	v_pk_mul_f32 v[16:17], v[16:17], v[192:193]
	v_pk_mul_f32 v[56:57], v[84:85], v[80:81]
	v_mul_f32_e32 v80, 0xbfb8aa3b, v73
	v_exp_f32_e32 v80, v80
	v_pk_mul_f32 v[16:17], v[16:17], v[56:57]
	v_rcp_f32_e32 v56, v49
	v_cvt_pk_bf16_f32 v236, v16, v17
	v_add_f32_e32 v49, 1.0, v80
	v_rcp_f32_e32 v57, v49
	v_pk_mul_f32 v[18:19], v[18:19], v[48:49] op_sel_hi:[1,0]
	v_pk_mul_f32 v[56:57], v[56:57], v[72:73]
	v_pk_mul_f32 v[18:19], v[18:19], v[194:195]
	s_nop 0
	v_pk_mul_f32 v[18:19], v[18:19], v[56:57]
	s_waitcnt lgkmcnt(6)
	v_lshlrev_b32_e32 v56, 16, v74
	v_and_b32_e32 v57, 0xffff0000, v74
	v_mul_f32_e32 v17, 0xbfb8aa3b, v56
	v_exp_f32_e32 v49, v17
	v_mul_f32_e32 v17, 0xbfb8aa3b, v57
	v_exp_f32_e32 v58, v17
	v_cvt_pk_bf16_f32 v237, v18, v19
	v_add_f32_e32 v18, 1.0, v49
	v_rcp_f32_e32 v18, v18
	v_add_f32_e32 v19, 1.0, v58
	v_rcp_f32_e32 v19, v19
	v_and_b32_e32 v252, 32, v205
	v_lshrrev_b32_e32 v252, 2, v252
	v_mov_b32_e32 v253, 0
	v_lshl_add_u64 v[254:255], v[142:143], 0, v[252:253]
	v_pk_mul_f32 v[16:17], v[20:21], v[48:49] op_sel_hi:[1,0]
	v_lshlrev_b32_e32 v20, 16, v75
	v_and_b32_e32 v21, 0xffff0000, v75
	v_pk_mul_f32 v[18:19], v[18:19], v[56:57]
	v_mul_f32_e32 v49, 0xbfb8aa3b, v20
	v_mul_f32_e32 v56, 0xbfb8aa3b, v21
	v_exp_f32_e32 v49, v49
	v_exp_f32_e32 v56, v56
	s_waitcnt vmcnt(4)
	v_pk_mul_f32 v[16:17], v[16:17], v[196:197]
	v_pk_mul_f32 v[22:23], v[22:23], v[48:49] op_sel_hi:[1,0]
	v_pk_mul_f32 v[16:17], v[16:17], v[18:19]
	v_add_f32_e32 v18, 1.0, v49
	v_add_f32_e32 v19, 1.0, v56
	v_rcp_f32_e32 v18, v18
	v_rcp_f32_e32 v19, v19
	v_cvt_pk_bf16_f32 v238, v16, v17
	v_pk_mul_f32 v[22:23], v[22:23], v[198:199]
	v_pk_mul_f32 v[0:1], v[0:1], v[48:49] op_sel_hi:[1,0]
	v_pk_mul_f32 v[18:19], v[18:19], v[20:21]
	s_waitcnt lgkmcnt(5)
	v_lshlrev_b32_e32 v20, 16, v76
	v_and_b32_e32 v21, 0xffff0000, v76
	v_mul_f32_e32 v17, 0xbfb8aa3b, v20
	v_pk_mul_f32 v[18:19], v[22:23], v[18:19]
	v_exp_f32_e32 v22, v17
	v_mul_f32_e32 v17, 0xbfb8aa3b, v21
	v_exp_f32_e32 v23, v17
	v_cvt_pk_bf16_f32 v239, v18, v19
	v_add_f32_e32 v18, 1.0, v22
	v_rcp_f32_e32 v18, v18
	v_add_f32_e32 v19, 1.0, v23
	v_rcp_f32_e32 v19, v19
	s_nop 1
	v_permlane32_swap_b32_e32 v236, v238
	v_permlane32_swap_b32_e32 v237, v239
	global_store_dwordx4 v[254:255], v[236:239], off
	v_pk_mul_f32 v[16:17], v[24:25], v[48:49] op_sel_hi:[1,0]
	s_waitcnt vmcnt(5)
	v_pk_mul_f32 v[0:1], v[0:1], v[216:217]
	v_pk_mul_f32 v[18:19], v[18:19], v[20:21]
	v_lshlrev_b32_e32 v20, 16, v77
	v_and_b32_e32 v21, 0xffff0000, v77
	v_mul_f32_e32 v22, 0xbfb8aa3b, v20
	v_mul_f32_e32 v23, 0xbfb8aa3b, v21
	v_exp_f32_e32 v22, v22
	v_exp_f32_e32 v23, v23
	v_pk_mul_f32 v[16:17], v[16:17], v[208:209]
	v_pk_mul_f32 v[2:3], v[2:3], v[48:49] op_sel_hi:[1,0]
	v_pk_mul_f32 v[16:17], v[16:17], v[18:19]
	v_add_f32_e32 v18, 1.0, v22
	v_add_f32_e32 v19, 1.0, v23
	v_rcp_f32_e32 v18, v18
	v_rcp_f32_e32 v19, v19
	v_pk_mul_f32 v[22:23], v[26:27], v[48:49] op_sel_hi:[1,0]
	v_cvt_pk_bf16_f32 v240, v16, v17
	v_pk_mul_f32 v[22:23], v[22:23], v[210:211]
	v_pk_mul_f32 v[18:19], v[18:19], v[20:21]
	s_waitcnt lgkmcnt(4)
	v_lshlrev_b32_e32 v20, 16, v78
	v_and_b32_e32 v21, 0xffff0000, v78
	v_mul_f32_e32 v17, 0xbfb8aa3b, v20
	v_pk_mul_f32 v[18:19], v[22:23], v[18:19]
	v_exp_f32_e32 v22, v17
	v_mul_f32_e32 v17, 0xbfb8aa3b, v21
	v_exp_f32_e32 v23, v17
	v_cvt_pk_bf16_f32 v241, v18, v19
	v_add_f32_e32 v18, 1.0, v22
	v_rcp_f32_e32 v18, v18
	v_add_f32_e32 v19, 1.0, v23
	v_rcp_f32_e32 v19, v19
	v_pk_mul_f32 v[16:17], v[28:29], v[48:49] op_sel_hi:[1,0]
	v_pk_mul_f32 v[2:3], v[2:3], v[218:219]
	v_pk_mul_f32 v[18:19], v[18:19], v[20:21]
	v_lshlrev_b32_e32 v20, 16, v79
	v_and_b32_e32 v21, 0xffff0000, v79
	v_mul_f32_e32 v22, 0xbfb8aa3b, v20
	v_mul_f32_e32 v23, 0xbfb8aa3b, v21
	v_exp_f32_e32 v22, v22
	v_exp_f32_e32 v23, v23
	v_pk_mul_f32 v[16:17], v[16:17], v[212:213]
	v_pk_mul_f32 v[6:7], v[6:7], v[48:49] op_sel_hi:[1,0]
	v_pk_mul_f32 v[16:17], v[16:17], v[18:19]
	v_add_f32_e32 v18, 1.0, v22
	v_add_f32_e32 v19, 1.0, v23
	v_rcp_f32_e32 v18, v18
	v_rcp_f32_e32 v19, v19
	v_pk_mul_f32 v[22:23], v[30:31], v[48:49] op_sel_hi:[1,0]
	v_cvt_pk_bf16_f32 v242, v16, v17
	v_pk_mul_f32 v[22:23], v[22:23], v[214:215]
	v_pk_mul_f32 v[18:19], v[18:19], v[20:21]
	s_waitcnt lgkmcnt(3)
	v_lshlrev_b32_e32 v20, 16, v82
	v_and_b32_e32 v21, 0xffff0000, v82
	v_mul_f32_e32 v17, 0xbfb8aa3b, v20
	v_pk_mul_f32 v[18:19], v[22:23], v[18:19]
	v_exp_f32_e32 v22, v17
	v_mul_f32_e32 v17, 0xbfb8aa3b, v21
	v_exp_f32_e32 v23, v17
	v_cvt_pk_bf16_f32 v243, v18, v19
	v_add_f32_e32 v18, 1.0, v22
	v_rcp_f32_e32 v18, v18
	v_add_f32_e32 v19, 1.0, v23
	v_rcp_f32_e32 v19, v19
	s_nop 1
	v_permlane32_swap_b32_e32 v240, v242
	v_permlane32_swap_b32_e32 v241, v243
	global_store_dwordx4 v[254:255], v[240:243], off offset:32
	s_waitcnt vmcnt(6)
	v_pk_mul_f32 v[6:7], v[6:7], v[222:223]
	v_pk_mul_f32 v[16:17], v[18:19], v[20:21]
	v_lshlrev_b32_e32 v18, 16, v83
	v_and_b32_e32 v19, 0xffff0000, v83
	v_mul_f32_e32 v20, 0xbfb8aa3b, v18
	v_mul_f32_e32 v21, 0xbfb8aa3b, v19
	v_exp_f32_e32 v20, v20
	v_exp_f32_e32 v21, v21
	v_pk_mul_f32 v[0:1], v[0:1], v[16:17]
	v_add_f32_e32 v16, 1.0, v20
	v_add_f32_e32 v17, 1.0, v21
	v_rcp_f32_e32 v16, v16
	v_rcp_f32_e32 v17, v17
	v_cvt_pk_bf16_f32 v244, v0, v1
	v_pk_mul_f32 v[16:17], v[16:17], v[18:19]
	s_nop 0
	v_pk_mul_f32 v[2:3], v[2:3], v[16:17]
	s_waitcnt lgkmcnt(2)
; DI unsigned pk_bf16(float lo, float hi) { f32x2 v = {lo, hi}; bf2_t b = __builtin_convertvector(v, bf2_t); return __builtin_bit_cast(unsigned, b); }
; DI float bf_lo(unsigned u) { return __uint_as_float(u << 16); }
; DI float bf_hi(unsigned u) { return __uint_as_float(u & 0xffff0000u); }
; DI float silu(float x) { return x * __builtin_amdgcn_rcpf(1.0f + __builtin_amdgcn_exp2f(-1.4426950408889634f * x)); }
; DI void store_head(const f32x16& o0, const f32x16& o1, float rs, const unsigned char* gl, int tr, int ch0, const float* gs, bf16_t* yp) {
;     ...
;     for (int q = 0; q < 8; ++q) { const int d = 32 * (q >> 2) + 8 * (q & 3), g = q & 3;
;         const f32x16& o = (q >> 2) ? o1 : o0;
;         u32x2 w; w.x = pk_bf16(o[4 * g + 0] * rs * gv[q][0] * silu(bf_lo(gt[q].x)), o[4 * g + 1] * rs * gv[q][1] * silu(bf_hi(gt[q].x)));
;         w.y = pk_bf16(o[4 * g + 2] * rs * gv[q][2] * silu(bf_lo(gt[q].y)), o[4 * g + 3] * rs * gv[q][3] * silu(bf_hi(gt[q].y)));
;         *(u32x2*)(yp + d) = w; }
	v_lshlrev_b32_e32 v16, 16, v54
	v_and_b32_e32 v17, 0xffff0000, v54
	v_mul_f32_e32 v1, 0xbfb8aa3b, v16
	v_exp_f32_e32 v18, v1
	v_mul_f32_e32 v1, 0xbfb8aa3b, v17
	v_exp_f32_e32 v19, v1
	v_cvt_pk_bf16_f32 v245, v2, v3
	v_add_f32_e32 v2, 1.0, v18
	v_rcp_f32_e32 v2, v2
	v_add_f32_e32 v3, 1.0, v19
	v_rcp_f32_e32 v3, v3
	v_pk_mul_f32 v[0:1], v[4:5], v[48:49] op_sel_hi:[1,0]
	v_lshlrev_b32_e32 v4, 16, v55
	v_and_b32_e32 v5, 0xffff0000, v55
	v_pk_mul_f32 v[2:3], v[2:3], v[16:17]
	v_mul_f32_e32 v16, 0xbfb8aa3b, v4
	v_mul_f32_e32 v17, 0xbfb8aa3b, v5
	v_exp_f32_e32 v16, v16
	v_exp_f32_e32 v17, v17
	v_pk_mul_f32 v[0:1], v[0:1], v[220:221]
	s_nop 0
	v_pk_mul_f32 v[0:1], v[0:1], v[2:3]
	v_add_f32_e32 v2, 1.0, v16
	v_add_f32_e32 v3, 1.0, v17
	v_rcp_f32_e32 v2, v2
	v_rcp_f32_e32 v3, v3
	v_cvt_pk_bf16_f32 v246, v0, v1
	v_pk_mul_f32 v[2:3], v[2:3], v[4:5]
	s_waitcnt lgkmcnt(1)
	v_lshlrev_b32_e32 v4, 16, v52
	v_and_b32_e32 v5, 0xffff0000, v52
	v_mul_f32_e32 v1, 0xbfb8aa3b, v4
	v_pk_mul_f32 v[2:3], v[6:7], v[2:3]
	v_exp_f32_e32 v6, v1
	v_mul_f32_e32 v1, 0xbfb8aa3b, v5
	v_exp_f32_e32 v7, v1
	v_cvt_pk_bf16_f32 v247, v2, v3
	v_add_f32_e32 v2, 1.0, v6
	v_rcp_f32_e32 v2, v2
	v_add_f32_e32 v3, 1.0, v7
	v_rcp_f32_e32 v3, v3
	s_nop 1
	v_permlane32_swap_b32_e32 v244, v246
	v_permlane32_swap_b32_e32 v245, v247
	global_store_dwordx4 v[254:255], v[244:247], off offset:64
	v_pk_mul_f32 v[0:1], v[8:9], v[48:49] op_sel_hi:[1,0]
	v_pk_mul_f32 v[2:3], v[2:3], v[4:5]
	v_lshlrev_b32_e32 v4, 16, v53
	v_and_b32_e32 v5, 0xffff0000, v53
	v_mul_f32_e32 v6, 0xbfb8aa3b, v4
	v_mul_f32_e32 v7, 0xbfb8aa3b, v5
	v_exp_f32_e32 v6, v6
	v_exp_f32_e32 v7, v7
	s_waitcnt vmcnt(7)
	v_pk_mul_f32 v[0:1], v[0:1], v[224:225]
	s_nop 0
	v_pk_mul_f32 v[0:1], v[0:1], v[2:3]
	v_add_f32_e32 v2, 1.0, v6
	v_add_f32_e32 v3, 1.0, v7
	v_rcp_f32_e32 v2, v2
	v_rcp_f32_e32 v3, v3
	v_pk_mul_f32 v[6:7], v[10:11], v[48:49] op_sel_hi:[1,0]
	v_cvt_pk_bf16_f32 v248, v0, v1
	v_pk_mul_f32 v[6:7], v[6:7], v[226:227]
	v_pk_mul_f32 v[2:3], v[2:3], v[4:5]
	s_waitcnt lgkmcnt(0)
	v_lshlrev_b32_e32 v4, 16, v50
	v_and_b32_e32 v5, 0xffff0000, v50
	v_mul_f32_e32 v1, 0xbfb8aa3b, v4
	v_pk_mul_f32 v[2:3], v[6:7], v[2:3]
	v_exp_f32_e32 v6, v1
	v_mul_f32_e32 v1, 0xbfb8aa3b, v5
	v_exp_f32_e32 v7, v1
	v_cvt_pk_bf16_f32 v249, v2, v3
	v_add_f32_e32 v2, 1.0, v6
	v_rcp_f32_e32 v2, v2
	v_add_f32_e32 v3, 1.0, v7
	v_rcp_f32_e32 v3, v3
	v_pk_mul_f32 v[0:1], v[12:13], v[48:49] op_sel_hi:[1,0]
	v_pk_mul_f32 v[2:3], v[2:3], v[4:5]
	v_lshlrev_b32_e32 v4, 16, v51
	v_and_b32_e32 v5, 0xffff0000, v51
	v_mul_f32_e32 v6, 0xbfb8aa3b, v4
	v_mul_f32_e32 v7, 0xbfb8aa3b, v5
	v_exp_f32_e32 v6, v6
	v_exp_f32_e32 v7, v7
	s_waitcnt vmcnt(7)
	v_pk_mul_f32 v[0:1], v[0:1], v[228:229]
	s_nop 0
	v_pk_mul_f32 v[0:1], v[0:1], v[2:3]
	v_add_f32_e32 v2, 1.0, v6
	v_add_f32_e32 v3, 1.0, v7
	v_rcp_f32_e32 v2, v2
	v_rcp_f32_e32 v3, v3
	v_pk_mul_f32 v[6:7], v[14:15], v[48:49] op_sel_hi:[1,0]
	v_cvt_pk_bf16_f32 v250, v0, v1
	v_pk_mul_f32 v[6:7], v[6:7], v[230:231]
	v_pk_mul_f32 v[2:3], v[2:3], v[4:5]
	s_nop 0
	v_pk_mul_f32 v[2:3], v[6:7], v[2:3]
	s_nop 0
	v_cvt_pk_bf16_f32 v251, v2, v3
	s_nop 1
	v_permlane32_swap_b32_e32 v248, v250
	v_permlane32_swap_b32_e32 v249, v251
	global_store_dwordx4 v[254:255], v[248:251], off offset:96
	s_cbranch_vccz .LBB0_432
; DI void conv_tok(const ConvW& cw, const bf16_t* RR, int t, int ch, float (&y)[8]) {
;     const int t1 = t >= 1 ? t - 1 : 0, t2 = t >= 2 ? t - 2 : 0;
;     const float k1 = t >= 1 ? 1.f : 0.f, k2 = t >= 2 ? 1.f : 0.f;
;     const bf16_t* rp0 = RR + (size_t)t * 2048 + ch; const bf16_t* rp1 = RR + (size_t)t1 * 2048 + ch; const bf16_t* rp2 = RR + (size_t)t2 * 2048 + ch;
;     const u32x4 u0 = *(const u32x4*)rp0, b0 = *(const u32x4*)(rp0 + 256), c0 = *(const u32x4*)(rp0 + 512);
;     const u32x4 u1 = *(const u32x4*)rp1, c1 = *(const u32x4*)(rp1 + 512), u2 = *(const u32x4*)rp2, c2 = *(const u32x4*)(rp2 + 512);
; #pragma unroll
;     for (int e2 = 0; e2 < 4; ++e2) {
;         const int j = (2 * e2) & 3;
;         const f32x4& w0 = e2 < 2 ? cw.w0a : cw.w0b; const f32x4& w1 = e2 < 2 ? cw.w1a : cw.w1b; const f32x4& w2 = e2 < 2 ? cw.w2a : cw.w2b; const f32x4& bb = e2 < 2 ? cw.ba : cw.bb;
; DI void mixer_phase(const Params& p, unsigned char* ldsraw, int vid) {
;     ...
;                 const int cgp = wid - 4, chunk = ln & 7, trow = ln >> 3, ch = 64 * cgp + 8 * chunk;
;                 ConvW cw; { const float* wp = p.conv_w + ch; const float* bp = p.conv_b + ch;
;                     cw.w0a = *(const f32x4*)wp; cw.w0b = *(const f32x4*)(wp + 4); cw.w1a = *(const f32x4*)(wp + 256); cw.w1b = *(const f32x4*)(wp + 260);
;                     cw.w2a = *(const f32x4*)(wp + 512); cw.w2b = *(const f32x4*)(wp + 516); cw.ba = *(const f32x4*)bp; cw.bb = *(const f32x4*)(bp + 4); }
; #pragma unroll
;                 for (int j = 0; j < 8; ++j) {
;                     float y[8]; conv_tok(cw, RR, t0 + trow + 8 * j, ch, y);
;                     float ss = 0.f;
; #pragma unroll
;                     for (int e = 0; e < 8; ++e) ss += y[e] * y[e];
;                     ss += __shfl_xor(ss, 1); ss += __shfl_xor(ss, 2); ss += __shfl_xor(ss, 4);
;                     const int tk = trow + 8 * j;
;                     if (chunk == 0) lf[768 + 128 * (tk >> 5) + cgp * 32 + (tk & 31)] = ss;
;                     f32x16& dst = (j < 2) ? a0 : (j < 4) ? a1 : (j < 6) ? b0 : b1;
; #pragma unroll
;                     for (int e = 0; e < 8; ++e) dst[(j & 1) * 8 + e] = y[e];
;                     if ((j & 3) == 3) __builtin_amdgcn_sched_barrier(0);
;                 }
	v_and_b32_e32 v69, 7, v205
	v_max_i32_e32 v0, 2, v146
	v_lshl_or_b32 v176, v69, 3, s93
	v_add_u32_e32 v0, -2, v0
	v_ashrrev_i32_e32 v147, 31, v146
	v_mov_b32_e32 v1, v177
	v_lshl_add_u64 v[32:33], v[176:177], 1, s[44:45]
	v_lshlrev_b64 v[2:3], 12, v[146:147]
	v_lshlrev_b64 v[0:1], 12, v[0:1]
	v_lshl_add_u64 v[2:3], v[32:33], 0, v[2:3]
	v_lshl_add_u64 v[0:1], v[32:33], 0, v[0:1]
	global_load_dwordx4 v[36:39], v[2:3], off offset:512
	global_load_dwordx4 v[40:43], v[0:1], off offset:1024
	global_load_dwordx4 v[44:47], v[2:3], off
	global_load_dwordx4 v[52:55], v[2:3], off offset:1024
	global_load_dwordx4 v[56:59], v[0:1], off
	v_max_i32_e32 v2, 1, v146
	v_lshlrev_b64 v[0:1], 2, v[176:177]
	v_add_u32_e32 v176, -1, v2
	v_lshlrev_b64 v[2:3], 12, v[176:177]
	v_lshl_add_u64 v[2:3], v[32:33], 0, v[2:3]
	global_load_dwordx4 v[60:63], v[2:3], off
	global_load_dwordx4 v[64:67], v[2:3], off offset:1024
	v_lshl_add_u64 v[2:3], s[48:49], 0, v[0:1]
	global_load_dwordx4 v[28:31], v[2:3], off
	global_load_dwordx4 v[24:27], v[2:3], off offset:1024
	global_load_dwordx4 v[16:19], v[2:3], off offset:2048
	v_lshl_add_u64 v[4:5], s[50:51], 0, v[0:1]
	global_load_dwordx4 v[20:23], v[4:5], off
	global_load_dwordx4 v[12:15], v[2:3], off offset:16
	global_load_dwordx4 v[8:11], v[2:3], off offset:1040
	s_nop 0
	global_load_dwordx4 v[0:3], v[2:3], off offset:2064
	s_nop 0
	global_load_dwordx4 v[4:7], v[4:5], off offset:16
	v_cmp_lt_i32_e32 vcc, 0, v146
	v_xor_b32_e32 v34, 1, v202
	s_waitcnt vmcnt(13)
	v_lshlrev_b32_e32 v50, 16, v40
	v_cndmask_b32_e64 v68, 0, 1.0, vcc
	v_cmp_lt_i32_e32 vcc, 1, v146
	s_waitcnt vmcnt(10)
	v_lshlrev_b32_e32 v78, 16, v56
	v_and_b32_e32 v79, 0xffff0000, v56
	v_cndmask_b32_e64 v70, 0, 1.0, vcc
	v_lshlrev_b32_e32 v56, 16, v57
	v_and_b32_e32 v57, 0xffff0000, v57
	v_and_b32_e32 v51, 0xffff0000, v40
	v_lshlrev_b32_e32 v72, 16, v44
	v_and_b32_e32 v73, 0xffff0000, v44
	v_lshlrev_b32_e32 v74, 16, v52
	v_and_b32_e32 v75, 0xffff0000, v52
	v_lshlrev_b32_e32 v40, 16, v41
	v_and_b32_e32 v41, 0xffff0000, v41
	v_lshlrev_b32_e32 v44, 16, v45
	v_and_b32_e32 v45, 0xffff0000, v45
	v_lshlrev_b32_e32 v52, 16, v53
	v_and_b32_e32 v53, 0xffff0000, v53
	s_waitcnt vmcnt(9)
	v_lshlrev_b32_e32 v82, 16, v60
	v_and_b32_e32 v83, 0xffff0000, v60
	v_lshlrev_b32_e32 v60, 16, v61
	v_and_b32_e32 v61, 0xffff0000, v61
	v_pk_mul_f32 v[56:57], v[70:71], v[56:57] op_sel_hi:[0,1]
	s_waitcnt vmcnt(8)
	v_lshlrev_b32_e32 v84, 16, v64
	v_and_b32_e32 v85, 0xffff0000, v64
	v_lshlrev_b32_e32 v64, 16, v65
	v_and_b32_e32 v65, 0xffff0000, v65
	v_pk_mul_f32 v[44:45], v[44:45], v[52:53]
	v_pk_mul_f32 v[52:53], v[70:71], v[78:79] op_sel_hi:[0,1]
	v_pk_mul_f32 v[60:61], v[68:69], v[60:61] op_sel_hi:[0,1]
	v_pk_mul_f32 v[40:41], v[56:57], v[40:41]
	v_pk_mul_f32 v[72:73], v[72:73], v[74:75]
	v_pk_mul_f32 v[74:75], v[68:69], v[82:83] op_sel_hi:[0,1]
	v_pk_mul_f32 v[50:51], v[52:53], v[50:51]
	v_pk_mul_f32 v[56:57], v[60:61], v[64:65]
	s_waitcnt vmcnt(7)
	v_pk_mul_f32 v[40:41], v[30:31], v[40:41]
	v_pk_mul_f32 v[52:53], v[74:75], v[84:85]
	v_pk_mul_f32 v[50:51], v[28:29], v[50:51]
	s_waitcnt vmcnt(6)
	v_pk_fma_f32 v[40:41], v[26:27], v[56:57], v[40:41]
	v_pk_fma_f32 v[50:51], v[24:25], v[52:53], v[50:51]
	s_waitcnt vmcnt(5)
	v_pk_fma_f32 v[40:41], v[18:19], v[44:45], v[40:41]
	v_lshlrev_b32_e32 v48, 16, v36
	v_and_b32_e32 v49, 0xffff0000, v36
	v_lshlrev_b32_e32 v36, 16, v37
	v_and_b32_e32 v37, 0xffff0000, v37
	v_lshlrev_b32_e32 v80, 16, v58
	v_and_b32_e32 v81, 0xffff0000, v58
	v_pk_fma_f32 v[50:51], v[16:17], v[72:73], v[50:51]
	s_waitcnt vmcnt(4)
	v_pk_add_f32 v[40:41], v[22:23], v[40:41]
	v_pk_add_f32 v[44:45], v[20:21], v[50:51]
	v_pk_mul_f32 v[50:51], v[40:41], v[36:37]
	v_pk_mul_f32 v[36:37], v[70:71], v[80:81] op_sel_hi:[0,1]
	v_lshlrev_b32_e32 v40, 16, v42
	v_and_b32_e32 v41, 0xffff0000, v42
	v_pk_mul_f32 v[36:37], v[36:37], v[40:41]
	v_lshlrev_b32_e32 v40, 16, v62
	v_and_b32_e32 v41, 0xffff0000, v62
	v_pk_mul_f32 v[48:49], v[44:45], v[48:49]
	v_pk_mul_f32 v[40:41], v[68:69], v[40:41] op_sel_hi:[0,1]
	v_lshlrev_b32_e32 v44, 16, v66
	v_and_b32_e32 v45, 0xffff0000, v66
	s_waitcnt vmcnt(3)
	v_pk_mul_f32 v[36:37], v[12:13], v[36:37]
	v_pk_mul_f32 v[40:41], v[40:41], v[44:45]
	v_lshlrev_b32_e32 v44, 16, v54
	s_waitcnt vmcnt(2)
	v_pk_fma_f32 v[36:37], v[8:9], v[40:41], v[36:37]
	v_lshlrev_b32_e32 v40, 16, v46
	v_and_b32_e32 v41, 0xffff0000, v46
	v_and_b32_e32 v45, 0xffff0000, v54
	v_pk_mul_f32 v[40:41], v[40:41], v[44:45]
	v_lshlrev_b32_e32 v76, 16, v38
	s_waitcnt vmcnt(1)
	v_pk_fma_f32 v[36:37], v[0:1], v[40:41], v[36:37]
	v_and_b32_e32 v77, 0xffff0000, v38
	s_waitcnt vmcnt(0)
	v_pk_add_f32 v[36:37], v[4:5], v[36:37]
	v_lshlrev_b32_e32 v38, 16, v59
	v_pk_mul_f32 v[52:53], v[36:37], v[76:77]
	v_lshlrev_b32_e32 v36, 16, v39
	v_and_b32_e32 v37, 0xffff0000, v39
	v_and_b32_e32 v39, 0xffff0000, v59
	v_pk_mul_f32 v[38:39], v[70:71], v[38:39] op_sel_hi:[0,1]
	v_lshlrev_b32_e32 v40, 16, v43
	v_and_b32_e32 v41, 0xffff0000, v43
	v_pk_mul_f32 v[38:39], v[38:39], v[40:41]
	v_lshlrev_b32_e32 v40, 16, v63
	v_and_b32_e32 v41, 0xffff0000, v63
	v_pk_mul_f32 v[40:41], v[68:69], v[40:41] op_sel_hi:[0,1]
	v_lshlrev_b32_e32 v42, 16, v67
	v_and_b32_e32 v43, 0xffff0000, v67
	v_pk_mul_f32 v[38:39], v[14:15], v[38:39]
	v_pk_mul_f32 v[40:41], v[40:41], v[42:43]
	v_lshlrev_b32_e32 v42, 16, v55
	v_pk_fma_f32 v[38:39], v[10:11], v[40:41], v[38:39]
	v_lshlrev_b32_e32 v40, 16, v47
	v_and_b32_e32 v41, 0xffff0000, v47
	v_and_b32_e32 v43, 0xffff0000, v55
	v_pk_mul_f32 v[40:41], v[40:41], v[42:43]
	v_cmp_lt_i32_e32 vcc, v34, v204
	v_pk_fma_f32 v[38:39], v[2:3], v[40:41], v[38:39]
	v_pk_mul_f32 v[40:41], v[52:53], v[52:53]
	v_pk_add_f32 v[38:39], v[6:7], v[38:39]
	v_cndmask_b32_e32 v34, v202, v34, vcc
	v_pk_mul_f32 v[54:55], v[38:39], v[36:37]
	v_pk_mul_f32 v[36:37], v[48:49], v[48:49]
	v_pk_mul_f32 v[38:39], v[50:51], v[50:51]
	v_add_f32_e32 v35, v36, v37
	v_add_f32_e32 v35, v38, v35
	v_add_f32_e32 v35, v39, v35
	v_add_f32_e32 v35, v40, v35
	v_pk_mul_f32 v[42:43], v[54:55], v[54:55]
	v_add_f32_e32 v35, v41, v35
	v_add_f32_e32 v35, v42, v35
	v_lshlrev_b32_e32 v34, 2, v34
	v_add_f32_e32 v36, v43, v35
	ds_bpermute_b32 v37, v34, v36
	v_xor_b32_e32 v35, 2, v202
	v_cmp_lt_i32_e32 vcc, v35, v204
	s_waitcnt lgkmcnt(0)
	v_add_f32_e32 v37, v36, v37
	v_cndmask_b32_e32 v35, v202, v35, vcc
	v_lshlrev_b32_e32 v35, 2, v35
	ds_bpermute_b32 v38, v35, v37
	v_xor_b32_e32 v36, 4, v202
	v_cmp_lt_i32_e32 vcc, v36, v204
	s_waitcnt lgkmcnt(0)
	v_add_f32_e32 v38, v37, v38
	v_cndmask_b32_e32 v36, v202, v36, vcc
	v_lshlrev_b32_e32 v36, 2, v36
	ds_bpermute_b32 v39, v36, v38
	v_cmp_eq_u32_e32 vcc, 0, v69
	v_and_b32_e32 v37, 0xfffffe00, v164
	s_and_saveexec_b64 s[0:1], vcc
	s_cbranch_execz .LBB0_417
	v_lshrrev_b32_e32 v40, 1, v205
	v_and_b32_e32 v40, 0x7c, v40
	v_add3_u32 v40, s75, v37, v40
	s_waitcnt lgkmcnt(0)
	v_add_f32_e32 v38, v38, v39
	ds_write_b32 v40, v38 offset:3072
